# P4: blocks with bit3 of id set run scan items first and DFT GEMM (atomic epilogue) last
# speedup vs baseline: 1.0077x; 1.0043x over previous
.LBB0_449:
	s_or_b64 exec, exec, s[0:1]
	v_writelane_b32 v253, s76, 42
	s_cmpk_gt_i32 s55, 0x23f
	s_waitcnt lgkmcnt(0)
	v_writelane_b32 v253, s77, 43
	v_writelane_b32 v253, s78, 44
	v_writelane_b32 v253, s79, 45
	v_writelane_b32 v253, s80, 46
	v_writelane_b32 v253, s81, 47
	v_writelane_b32 v253, s82, 48
	v_writelane_b32 v253, s83, 49
	s_barrier
	s_cbranch_scc1 .LBB0_494
	s_bitcmp1_b32 s55, 3
	s_cselect_b32 s98, 1, 0
	v_writelane_b32 v255, s98, 47
	s_cbranch_scc1 .LBB0_494
.Lp4_gemm_pre:
	s_add_u32 s10, s44, 0x400000
	s_addc_u32 s11, s45, 0
	s_add_u32 s4, s44, 0x4c0100
	s_addc_u32 s5, s45, 0
	s_lshl_b32 s12, s55, 9
	s_lshl_b32 s13, s92, 9
	s_lshl_b32 s14, s55, 3
	s_lshl_b32 s15, s92, 3
	s_mov_b32 s7, 0
	v_mov_b32_e32 v101, 0
	s_movk_i32 s16, 0x70
	s_mov_b32 s17, s55
	s_branch .LBB0_453

.LBB0_696:
	v_readlane_b32 s98, v255, 47
	s_nop 1
	s_cmp_eq_u32 s98, 1
	s_cbranch_scc0 .Lp4_noswap
	s_mov_b32 s98, 2
	v_writelane_b32 v255, s98, 47
	v_readlane_b32 s98, v253, 4
	v_readlane_b32 s99, v253, 5
	s_nop 1
	s_sub_u32 s98, s98, 0x228
	s_subb_u32 s99, s99, 0
	s_load_dwordx4 s[44:47], s[98:99], 0x178
	s_waitcnt lgkmcnt(0)
	s_branch .Lp4_gemm_pre
.Lp4_gemm_exit:
	v_readlane_b32 s98, v255, 47
	s_nop 1
	s_cmp_eq_u32 s98, 2
	s_cbranch_scc0 .LBB0_494
